# phase 7: every other group of eight workgroups starts its scan unit one s_sleep 127 late
# baseline (speedup 1.0000x reference)
.LBB0_897:
	s_cmp_lt_i32 s68, 8
	s_cselect_b64 s[6:7], -1, 0
	s_and_b64 s[48:49], s[6:7], s[4:5]
	s_andn2_b64 vcc, exec, s[48:49]
	s_cbranch_vccnz .LBB0_941
	s_cmpk_gt_i32 s2, 0xff
	s_cbranch_scc1 .LBB0_941
	s_cmpk_lg_u32 s70, 0x100
	s_cbranch_scc1 .Lp7_go
	s_bitcmp1_b32 s2, 3
	s_cbranch_scc0 .Lp7_go
	s_sleep 127
.Lp7_go:
	v_lshrrev_b32_e32 v85, 8, v1
	s_mov_b32 s5, 0x9600
	v_lshrrev_b32_e32 v2, 1, v1
	v_and_b32_e32 v32, 31, v1
	v_mad_u32_u24 v33, v85, s5, 0
	s_movk_i32 s5, 0x60
	v_bfe_u32 v3, v1, 5, 1
	v_and_or_b32 v36, v2, s5, v32
	v_lshlrev_b32_e32 v131, 4, v3
	v_lshlrev_b32_e32 v34, 1, v36
	s_movk_i32 s8, 0x50
	s_movk_i32 s33, 0x110
	s_movk_i32 s4, 0x100
	v_add_u32_e32 v39, v33, v34
	v_mad_u32_u24 v132, v36, s8, v33
	v_add_u32_e32 v133, v33, v131
	v_mad_u32_u24 v135, v32, s33, v33
	v_lshlrev_b32_e32 v33, 2, v3
	s_add_i32 s42, 0, 0x12c00
	v_cmp_gt_u32_e64 s[4:5], s4, v1
	v_add_u32_e32 v84, s42, v34
	v_xor_b32_e32 v34, 31, v33
	v_mov_b32_e32 v2, 0xfffffc00
	v_mov_b32_e32 v4, 0x400
	v_cndmask_b32_e64 v138, v34, v33, s[4:5]
	v_or_b32_e32 v34, 2, v33
	v_cndmask_b32_e64 v130, v2, v4, s[4:5]
	v_xor_b32_e32 v2, 31, v131
	v_mov_b32_e32 v37, 0xe0
	v_cmp_gt_u32_e64 s[12:13], v34, v32
	v_or_b32_e32 v34, 3, v33
	v_cndmask_b32_e64 v4, v37, 0, s[4:5]
	v_cndmask_b32_e64 v38, v2, v131, s[4:5]
	v_cmp_gt_u32_e64 s[14:15], v34, v32
	v_or_b32_e32 v34, 8, v33
	v_mbcnt_lo_u32_b32 v46, -1, 0
	v_or_b32_e32 v2, v38, v4
	v_cmp_gt_u32_e64 s[16:17], v34, v32
	v_or_b32_e32 v34, 9, v33
	v_mbcnt_hi_u32_b32 v46, -1, v46
	v_lshl_or_b32 v2, v2, 10, v36
	v_cmp_gt_u32_e64 s[18:19], v34, v32
	v_or_b32_e32 v34, 10, v33
	v_and_b32_e32 v48, 64, v46
	v_add_u32_e32 v82, v2, v130
	v_cmp_gt_u32_e64 s[20:21], v34, v32
	v_or_b32_e32 v34, 11, v33
	v_xor_b32_e32 v47, 32, v46
	v_add_u32_e32 v48, 64, v48
	v_add_u32_e32 v4, v82, v130
	v_cmp_gt_u32_e64 s[22:23], v34, v32
	v_or_b32_e32 v34, 16, v33
	v_cmp_lt_i32_e32 vcc, v47, v48
	v_add_u32_e32 v6, v4, v130
	v_cmp_gt_u32_e64 s[24:25], v34, v32
	v_or_b32_e32 v34, 17, v33
	v_cndmask_b32_e32 v47, v46, v47, vcc
	v_add_u32_e32 v8, v6, v130
	v_cmp_gt_u32_e64 s[26:27], v34, v32
	v_or_b32_e32 v34, 18, v33
	v_lshlrev_b32_e32 v154, 2, v47
	v_xor_b32_e32 v47, 8, v46
	v_add_u32_e32 v10, v8, v130
	v_cmp_gt_u32_e64 s[28:29], v34, v32
	v_or_b32_e32 v34, 19, v33
	v_cmp_lt_i32_e32 vcc, v47, v48
	v_add_u32_e32 v12, v10, v130
	v_cmp_gt_u32_e64 s[30:31], v34, v32
	v_or_b32_e32 v34, 24, v33
	v_cndmask_b32_e32 v47, v46, v47, vcc
	v_add_u32_e32 v14, v12, v130
	v_cmp_gt_u32_e64 s[34:35], v34, v32
	v_or_b32_e32 v34, 25, v33
	v_lshlrev_b32_e32 v155, 2, v47
	v_xor_b32_e32 v47, 4, v46
	v_add_u32_e32 v16, v14, v130
	v_mov_b32_e32 v35, 0xfffffef0
	v_mov_b32_e32 v42, 0x110
	v_cmp_gt_u32_e64 s[36:37], v34, v32
	v_or_b32_e32 v34, 26, v33
	v_cmp_lt_i32_e32 vcc, v47, v48
	v_mov_b32_e32 v83, 0
	v_add_u32_e32 v18, v16, v130
	v_cndmask_b32_e64 v137, v35, v42, s[4:5]
	v_cmp_gt_u32_e64 s[8:9], v33, v32
	v_cmp_lt_u32_e64 s[10:11], v33, v32
	v_cmp_gt_u32_e64 s[38:39], v34, v32
	v_or_b32_e32 v33, 27, v33
	v_mov_b32_e32 v34, 0x7c00000
	v_mov_b32_e32 v35, 0x5c00000
	v_cndmask_b32_e32 v47, v46, v47, vcc
	v_add_u32_e32 v20, v18, v130
	v_mul_u32_u24_e32 v41, 0x110, v32
	v_cmp_gt_u32_e64 s[40:41], v33, v32
	v_mul_u32_u24_e32 v43, 0x50, v32
	v_lshlrev_b32_e32 v32, 3, v1
	v_cndmask_b32_e64 v34, v34, v35, s[4:5]
	v_mov_b32_e32 v35, v83
	v_lshlrev_b32_e32 v156, 2, v47
	v_xor_b32_e32 v47, 2, v46
	v_add_u32_e32 v22, v20, v130
	v_and_b32_e32 v33, 0x78, v32
	v_cmp_lt_i32_e32 vcc, v47, v48
	v_lshl_add_u64 v[86:87], s[66:67], 0, v[34:35]
	v_lshlrev_b32_e32 v34, 2, v36
	v_add_u32_e32 v24, v22, v130
	v_lshlrev_b32_e32 v32, 1, v33
	v_cndmask_b32_e32 v47, v46, v47, vcc
	v_lshl_or_b32 v34, v3, 11, v34
	v_add_u32_e32 v26, v24, v130
	v_add_u32_e32 v44, s42, v32
	v_lshlrev_b32_e32 v157, 2, v47
	v_xor_b32_e32 v47, 1, v46
	s_add_u32 s55, s66, 0x3c00000
	v_lshl_add_u64 v[34:35], s[66:67], 0, v[34:35]
	s_mov_b64 s[42:43], 0x1c00000
	v_add_u32_e32 v28, v26, v130
	v_cmp_eq_u32_e64 s[6:7], 0, v3
	v_lshlrev_b32_e32 v40, 5, v3
	v_lshlrev_b32_e32 v136, 3, v3
	v_mul_u32_u24_e32 v42, 0x1100, v3
	v_lshrrev_b32_e32 v153, 4, v1
	v_cmp_lt_i32_e32 vcc, v47, v48
	s_addc_u32 s74, s67, 0
	v_lshl_add_u64 v[88:89], v[34:35], 0, s[42:43]
	v_cndmask_b32_e64 v3, 0, v37, s[4:5]
	v_lshlrev_b32_e32 v34, 2, v33
	v_readlane_b32 s80, v240, 6
	v_mov_b32_e32 v33, v83
	v_mov_b32_e32 v5, v83
	v_mov_b32_e32 v7, v83
	v_mov_b32_e32 v9, v83
	v_mov_b32_e32 v11, v83
	v_mov_b32_e32 v13, v83
	v_mov_b32_e32 v15, v83
	v_mov_b32_e32 v17, v83
	v_mov_b32_e32 v19, v83
	v_mov_b32_e32 v21, v83
	v_mov_b32_e32 v23, v83
	v_mov_b32_e32 v25, v83
	v_mov_b32_e32 v27, v83
	v_mov_b32_e32 v29, v83
	v_add_u32_e32 v30, v28, v130
	v_mov_b32_e32 v31, v83
	v_mul_u32_u24_e32 v45, 0x110, v153
	v_cndmask_b32_e32 v46, v46, v47, vcc
	s_add_u32 s75, s66, 0x9c00000
	v_or_b32_e32 v3, v3, v138
	v_mov_b32_e32 v35, v83
	v_readlane_b32 s81, v240, 7
	v_readlane_b32 s82, v240, 8
	v_readlane_b32 s83, v240, 9
	v_readlane_b32 s84, v240, 10
	v_readlane_b32 s85, v240, 11
	v_readlane_b32 s86, v240, 12
	v_readlane_b32 s87, v240, 13
	v_readlane_b32 s88, v240, 14
	v_readlane_b32 s89, v240, 15
	v_readlane_b32 s90, v240, 16
	v_readlane_b32 s91, v240, 17
	v_readlane_b32 s92, v240, 18
	v_readlane_b32 s93, v240, 19
	v_readlane_b32 s94, v240, 20
	v_readlane_b32 s95, v240, 21
	v_lshl_add_u64 v[32:33], s[66:67], 0, v[32:33]
	s_mov_b64 s[42:43], 0xbc00000
	s_mov_b32 s53, 0
	v_mul_i32_i24_e32 v134, 0xffffffb4, v36
	v_lshlrev_b32_e32 v139, 1, v137
	v_mul_i32_i24_e32 v140, 3, v137
	v_lshlrev_b32_e32 v141, 3, v137
	v_mul_i32_i24_e32 v142, 9, v137
	v_mul_i32_i24_e32 v143, 10, v137
	v_mul_i32_i24_e32 v144, 11, v137
	v_lshlrev_b32_e32 v145, 4, v137
	v_mul_i32_i24_e32 v146, 17, v137
	v_mul_i32_i24_e32 v147, 18, v137
	v_mul_i32_i24_e32 v148, 19, v137
	v_mul_i32_i24_e32 v149, 24, v137
	v_mul_i32_i24_e32 v150, 25, v137
	v_mul_i32_i24_e32 v151, 26, v137
	v_mul_i32_i24_e32 v152, 27, v137
	v_lshlrev_b32_e32 v158, 2, v46
	s_addc_u32 s76, s67, 0
	v_mad_u32_u24 v159, v3, s33, v84
	v_lshl_add_u64 v[90:91], s[82:83], 0, v[34:35]
	v_lshl_add_u64 v[92:93], v[32:33], 0, s[42:43]
	v_lshl_or_b32 v160, v38, 10, v36
	s_movk_i32 s51, 0x1000
	s_movk_i32 s77, 0x2000
	s_movk_i32 s78, 0x3000
	s_movk_i32 s79, 0x4000
	s_movk_i32 s80, 0x5000
	s_movk_i32 s81, 0x6000
	s_movk_i32 s82, 0x7000
	s_mov_b32 s83, 0x8000
	s_mov_b32 s84, 0x9000
	s_mov_b32 s85, 0xa000
	s_mov_b32 s86, 0xb000
	s_mov_b32 s87, 0xc000
	s_mov_b32 s88, 0xd000
	s_mov_b32 s89, 0xe000
	s_mov_b32 s90, 0xf000
	v_lshlrev_b32_e32 v94, 1, v2
	v_lshlrev_b64 v[96:97], 1, v[82:83]
	v_lshlrev_b64 v[98:99], 1, v[4:5]
	v_lshlrev_b64 v[100:101], 1, v[6:7]
	v_lshlrev_b64 v[102:103], 1, v[8:9]
	v_lshlrev_b64 v[104:105], 1, v[10:11]
	v_lshlrev_b64 v[106:107], 1, v[12:13]
	v_lshlrev_b64 v[108:109], 1, v[14:15]
	v_lshlrev_b64 v[110:111], 1, v[16:17]
	v_lshlrev_b64 v[112:113], 1, v[18:19]
	v_lshlrev_b64 v[114:115], 1, v[20:21]
	v_lshlrev_b64 v[116:117], 1, v[22:23]
	v_lshlrev_b64 v[118:119], 1, v[24:25]
	v_lshlrev_b64 v[120:121], 1, v[26:27]
	v_lshlrev_b64 v[122:123], 1, v[28:29]
	v_lshlrev_b64 v[124:125], 1, v[30:31]
	v_add_u32_e32 v161, v133, v43
	v_add_u32_e32 v162, v44, v45
	s_mov_b32 s91, 0x10000
	s_mov_b32 s92, 0x30000
	s_brev_b32 s50, 60
	s_mov_b32 s54, 0x358637bd
	s_mov_b32 s93, 0x800000
	s_mov_b32 s94, 0x50000
	v_add_u32_e32 v163, v39, v42
	v_add_u32_e32 v164, v132, v40
	v_add_u32_e32 v165, v133, v41
	s_mov_b32 s95, s2
	s_branch .LBB0_901
